# attention DMA issue block moved into the result-latency shadow after the last QK MFMA
# baseline (speedup 1.0000x reference)
.Latt_diff_p0:
.LBB0_107:
.LBB0_116:
	s_mul_i32 s30, s53, 0x2400
	v_add_u32_e32 v242, s30, v173
	ds_read_b128 v[112:115], v242 offset:0
	ds_read_b128 v[116:119], v242 offset:4608
	ds_read_b128 v[120:123], v242 offset:32
	ds_read_b128 v[124:127], v242 offset:4640
	ds_read_b128 v[202:205], v242 offset:64
	ds_read_b128 v[206:209], v242 offset:4672
	ds_read_b128 v[210:213], v242 offset:96
	ds_read_b128 v[214:217], v242 offset:4704
	s_mul_i32 s30, s53, 0x4800
	v_add_u32_e32 v243, s30, v174
	s_waitcnt lgkmcnt(7)
	v_mfma_f32_32x32x16_bf16 v[64:79], v[112:115], v[130:133], v[96:111]
	s_waitcnt lgkmcnt(6)
	v_mfma_f32_32x32x16_bf16 v[80:95], v[116:119], v[130:133], v[96:111]
	s_waitcnt lgkmcnt(5)
	v_mfma_f32_32x32x16_bf16 v[64:79], v[120:123], v[134:137], v[64:79]
	s_waitcnt lgkmcnt(4)
	v_mfma_f32_32x32x16_bf16 v[80:95], v[124:127], v[134:137], v[80:95]
	s_waitcnt lgkmcnt(3)
	v_mfma_f32_32x32x16_bf16 v[64:79], v[202:205], v[138:141], v[64:79]
	s_waitcnt lgkmcnt(2)
	v_mfma_f32_32x32x16_bf16 v[80:95], v[206:209], v[138:141], v[80:95]
	s_waitcnt lgkmcnt(1)
	v_mfma_f32_32x32x16_bf16 v[64:79], v[210:213], v[142:145], v[64:79]
	s_waitcnt lgkmcnt(0)
	v_mfma_f32_32x32x16_bf16 v[80:95], v[214:217], v[142:145], v[80:95]
	ds_read_b128 v[112:115], v243 offset:27648
	ds_read_b128 v[116:119], v243 offset:32256
	ds_read_b128 v[120:123], v243 offset:36864
	ds_read_b128 v[124:127], v243 offset:41472
	ds_read_b128 v[202:205], v243 offset:27680
	ds_read_b128 v[206:209], v243 offset:32288
	ds_read_b128 v[210:213], v243 offset:36896
	ds_read_b128 v[214:217], v243 offset:41504
	s_add_i32 s30, s52, 2
	s_cmp_ge_u32 s30, s21
	s_cselect_b64 s[46:47], -1, 0
	s_cbranch_scc1 .Latt_diff_dmaend
	s_cmp_lt_u32 s52, 2
	s_cselect_b32 s48, s45, s43
	s_mul_i32 s55, s50, 0x2400
	s_add_i32 s56, s55, s41
	s_mov_b32 m0, s56
	v_lshl_add_u32 v244, s48, 12, v153
	global_load_lds_dwordx4 v244, s[18:19]
	s_ashr_i32 s49, s48, 31
	s_lshl_b64 s[30:31], s[48:49], 1
	s_add_u32 s30, s39, s30
	s_addc_u32 s31, s42, s31
	s_add_i32 s55, s55, s56
	s_add_i32 m0, s55, 0x6c00
	v_lshl_add_u64 v[244:245], s[30:31], 0, v[150:151]
	global_load_lds_dwordx4 v[244:245], off
	s_add_i32 m0, s55, 0x8c00
	v_lshl_add_u64 v[244:245], s[30:31], 0, v[148:149]
	global_load_lds_dwordx4 v[244:245], off
	s_and_b64 vcc, exec, s[14:15]
	s_cbranch_vccz .Latt_diff_dmax
.Latt_diff_dmaend:
	s_cmp_eq_u32 s52, 0
	s_cselect_b32 s31, 0xff7fffff, 0
	v_max3_f32 v226, v64, v65, v66
	v_max3_f32 v227, v67, v68, v69
	v_max3_f32 v226, v226, v70, v71
	v_max3_f32 v227, v227, v72, v73
	v_max3_f32 v226, v226, v74, v75
	v_max3_f32 v227, v227, v76, v77
	v_max3_f32 v226, v226, v78, v79
	v_max3_f32 v228, v80, v81, v82
	v_max3_f32 v229, v83, v84, v85
	v_max3_f32 v228, v228, v86, v87
	v_max3_f32 v229, v229, v88, v89
	v_max3_f32 v228, v228, v90, v91
	v_max3_f32 v229, v229, v92, v93
	v_max3_f32 v228, v228, v94, v95
	v_max3_f32 v226, v226, v227, v228
	v_max_f32_e32 v226, v226, v229
	v_cmp_lt_f32_e32 vcc, s58, v226
	s_cmp_eq_u32 s52, 0
	s_cbranch_scc1 .Latt_diff_rare
	s_cbranch_vccz .Latt_diff_norescale

.Latt_mla_p0:
.LBB0_178:
.LBB0_191:
	s_mul_i32 s30, s56, 0x6400
	v_add_u32_e32 v209, s30, v246
	ds_read_b128 v[112:115], v209 offset:0
	ds_read_b128 v[116:119], v209 offset:12800
	ds_read_b128 v[120:123], v209 offset:32
	ds_read_b128 v[124:127], v209 offset:12832
	ds_read_b128 v[250:253], v209 offset:64
	s_mul_i32 s30, s56, 0x4800
	v_add_u32_e32 v219, s30, v247
	s_waitcnt lgkmcnt(4)
	v_mfma_f32_32x32x16_bf16 v[64:79], v[112:115], v[130:133], v[96:111]
	ds_read_b128 v[112:115], v209 offset:12864
	s_waitcnt lgkmcnt(4)
	v_mfma_f32_32x32x16_bf16 v[80:95], v[116:119], v[130:133], v[96:111]
	ds_read_b128 v[116:119], v209 offset:96
	s_waitcnt lgkmcnt(4)
	v_mfma_f32_32x32x16_bf16 v[64:79], v[120:123], v[134:137], v[64:79]
	ds_read_b128 v[120:123], v209 offset:12896
	s_waitcnt lgkmcnt(4)
	v_mfma_f32_32x32x16_bf16 v[80:95], v[124:127], v[134:137], v[80:95]
	ds_read_b128 v[124:127], v209 offset:128
	s_waitcnt lgkmcnt(4)
	v_mfma_f32_32x32x16_bf16 v[64:79], v[250:253], v[138:141], v[64:79]
	ds_read_b128 v[250:253], v209 offset:12928
	s_waitcnt lgkmcnt(4)
	v_mfma_f32_32x32x16_bf16 v[80:95], v[112:115], v[138:141], v[80:95]
	ds_read_b128 v[112:115], v209 offset:160
	s_waitcnt lgkmcnt(4)
	v_mfma_f32_32x32x16_bf16 v[64:79], v[116:119], v[142:145], v[64:79]
	ds_read_b128 v[116:119], v209 offset:12960
	s_waitcnt lgkmcnt(4)
	v_mfma_f32_32x32x16_bf16 v[80:95], v[120:123], v[142:145], v[80:95]
	ds_read_b128 v[120:123], v209 offset:192
	s_waitcnt lgkmcnt(4)
	v_mfma_f32_32x32x16_bf16 v[64:79], v[124:127], v[146:149], v[64:79]
	ds_read_b128 v[124:127], v209 offset:12992
	s_waitcnt lgkmcnt(4)
	v_mfma_f32_32x32x16_bf16 v[80:95], v[250:253], v[146:149], v[80:95]
	ds_read_b128 v[250:253], v209 offset:224
	s_waitcnt lgkmcnt(4)
	v_mfma_f32_32x32x16_bf16 v[64:79], v[112:115], v[150:153], v[64:79]
	ds_read_b128 v[112:115], v209 offset:13024
	s_waitcnt lgkmcnt(4)
	v_mfma_f32_32x32x16_bf16 v[80:95], v[116:119], v[150:153], v[80:95]
	ds_read_b128 v[116:119], v209 offset:256
	s_waitcnt lgkmcnt(4)
	v_mfma_f32_32x32x16_bf16 v[64:79], v[120:123], v[154:157], v[64:79]
	ds_read_b128 v[120:123], v209 offset:13056
	s_waitcnt lgkmcnt(4)
	v_mfma_f32_32x32x16_bf16 v[80:95], v[124:127], v[154:157], v[80:95]
	ds_read_b128 v[124:127], v209 offset:288
	s_waitcnt lgkmcnt(4)
	v_mfma_f32_32x32x16_bf16 v[64:79], v[250:253], v[158:161], v[64:79]
	ds_read_b128 v[250:253], v209 offset:13088
	s_waitcnt lgkmcnt(4)
	v_mfma_f32_32x32x16_bf16 v[80:95], v[112:115], v[158:161], v[80:95]
	ds_read_b128 v[112:115], v209 offset:320
	s_waitcnt lgkmcnt(4)
	v_mfma_f32_32x32x16_bf16 v[64:79], v[116:119], v[162:165], v[64:79]
	ds_read_b128 v[116:119], v209 offset:13120
	s_waitcnt lgkmcnt(4)
	v_mfma_f32_32x32x16_bf16 v[80:95], v[120:123], v[162:165], v[80:95]
	ds_read_b128 v[120:123], v209 offset:352
	s_waitcnt lgkmcnt(4)
	v_mfma_f32_32x32x16_bf16 v[64:79], v[124:127], v[166:169], v[64:79]
	ds_read_b128 v[124:127], v209 offset:13152
	s_waitcnt lgkmcnt(4)
	v_mfma_f32_32x32x16_bf16 v[80:95], v[250:253], v[166:169], v[80:95]
	s_waitcnt lgkmcnt(3)
	v_mfma_f32_32x32x16_bf16 v[64:79], v[112:115], v[170:173], v[64:79]
	s_waitcnt lgkmcnt(2)
	v_mfma_f32_32x32x16_bf16 v[80:95], v[116:119], v[170:173], v[80:95]
	s_waitcnt lgkmcnt(1)
	v_mfma_f32_32x32x16_bf16 v[64:79], v[120:123], v[174:177], v[64:79]
	s_waitcnt lgkmcnt(0)
	v_mfma_f32_32x32x16_bf16 v[80:95], v[124:127], v[174:177], v[80:95]
	ds_read_b128 v[112:115], v219 offset:0
	ds_read_b128 v[116:119], v219 offset:4608
	ds_read_b128 v[120:123], v219 offset:9216
	s_add_i32 s30, s55, 2
	s_cmp_ge_u32 s30, s20
	s_cselect_b64 s[60:61], -1, 0
	s_cbranch_scc1 .Latt_mla_dmaend
	s_cmp_lt_u32 s55, 2
	s_cselect_b32 s62, s51, s49
	s_mul_i32 s57, s52, 0x6400
	s_add_i32 s57, s57, s42
	s_mov_b32 m0, s57
	v_mad_u32_u24 v250, s62, v237, v222
	global_load_lds_dwordx4 v250, s[2:3]
	s_add_i32 m0, s57, 0x2000
	v_mad_u32_u24 v250, s62, v239, v224
	global_load_lds_dwordx4 v250, s[2:3]
	s_add_i32 m0, s57, 0x4000
	v_mad_u32_u24 v250, s62, v241, v226
	global_load_lds_dwordx4 v250, s[2:3]
	s_ashr_i32 s63, s62, 31
	s_lshl_b64 s[30:31], s[62:63], 1
	s_add_u32 s30, s21, s30
	s_addc_u32 s31, s43, s31
	s_mul_i32 s63, s52, 0x4800
	s_add_i32 s63, s63, s42
	s_add_i32 m0, s63, 0x12c00
	v_lshl_add_u64 v[250:251], s[30:31], 0, v[202:203]
	global_load_lds_dwordx4 v[250:251], off
	s_add_i32 m0, s63, 0x14c00
	v_lshl_add_u64 v[250:251], s[30:31], 0, v[200:201]
	global_load_lds_dwordx4 v[250:251], off
	s_and_b64 vcc, exec, s[18:19]
	s_cbranch_vccz .Latt_mla_dmax
.Latt_mla_dmaend:
	s_cmp_eq_u32 s55, 0
	s_cselect_b32 s31, 0xff7fffff, 0
	s_nop 1
	v_max3_f32 v209, v64, v65, v66
	v_max3_f32 v211, v67, v68, v69
	v_max3_f32 v209, v209, v70, v71
	v_max3_f32 v211, v211, v72, v73
	v_max3_f32 v209, v209, v74, v75
	v_max3_f32 v211, v211, v76, v77
	v_max3_f32 v209, v209, v78, v79
	v_max3_f32 v213, v80, v81, v82
	v_max3_f32 v215, v83, v84, v85
	v_max3_f32 v213, v213, v86, v87
	v_max3_f32 v215, v215, v88, v89
	v_max3_f32 v213, v213, v90, v91
	v_max3_f32 v215, v215, v92, v93
	v_max3_f32 v213, v213, v94, v95
	v_max3_f32 v209, v209, v211, v213
	v_max_f32_e32 v209, v209, v215
	v_cmp_lt_f32_e32 vcc, s58, v209
	s_cmp_eq_u32 s55, 0
	s_cbranch_scc1 .Latt_mla_rare
	s_cbranch_vccz .Latt_mla_norescale
